# v59 + whole-kernel code placement shifted by 8 bytes (2 s_nop executed once at entry), placement comparison with the 32-byte shift
# baseline (speedup 1.0000x reference)
_Z8mega_fwd4Args:
	s_nop 0
	s_nop 0
	s_mov_b64 s[70:71], s[0:1]
	s_load_dword s86, s[70:71], 0x128
	v_lshl_add_u32 v1, v0, 2, 0
	s_add_u32 s80, s70, 0x128
	v_add_u32_e32 v1, 0x20000, v1
	v_mov_b32_e32 v2, 0
	s_mov_b32 s82, s2
	v_readfirstlane_b32 s0, v0
	s_addc_u32 s81, s71, 0
	ds_write2st64_b32 v1, v2, v2 offset1:8
	ds_write2st64_b32 v1, v2, v2 offset0:16 offset1:24
	v_or_b32_e32 v1, 0x800, v0
	s_mov_b64 s[2:3], -1
	s_and_saveexec_b64 s[4:5], s[2:3]
	v_lshl_add_u32 v3, v1, 2, 0
	v_add_u32_e32 v3, 0x20000, v3
	ds_write_b32 v3, v2
	s_or_b64 exec, exec, s[4:5]
	s_and_saveexec_b64 s[4:5], s[2:3]
	s_add_i32 s1, 0, 0x20000
	v_lshl_add_u32 v1, v1, 2, s1
	v_mov_b32_e32 v2, 0
	ds_write_b32 v1, v2 offset:2048
	s_or_b64 exec, exec, s[4:5]
	s_load_dwordx2 s[72:73], s[70:71], 0xf8
	v_or_b32_e32 v1, 0xc00, v0
	v_cmp_gt_u32_e64 s[2:3], 7, 6
	v_cmp_gt_u32_e64 s[6:7], 7, 5
	s_and_saveexec_b64 s[4:5], s[6:7]
	v_lshl_add_u32 v2, v1, 2, 0
	v_add_u32_e32 v2, 0x20000, v2
	v_mov_b32_e32 v3, 0
	ds_write_b32 v2, v3
	s_or_b64 exec, exec, s[4:5]
	s_and_saveexec_b64 s[4:5], s[2:3]
	s_add_i32 s1, 0, 0x20000
	v_lshl_add_u32 v1, v1, 2, s1
	v_mov_b32_e32 v2, 0
	ds_write_b32 v1, v2 offset:2048
	s_or_b64 exec, exec, s[4:5]
	s_waitcnt lgkmcnt(0)
	s_barrier
	s_add_u32 s78, s72, 0x4000
	s_getreg_b32 s1, hwreg(HW_REG_XCC_ID, 0, 4)
	s_addc_u32 s79, s73, 0
	s_and_b32 s67, s1, 15
	v_cmp_eq_u32_e64 s[84:85], 0, v0
	s_and_saveexec_b64 s[2:3], s[84:85]
	s_cbranch_execz .LBB0_11
	s_mov_b64 s[4:5], exec
	v_mbcnt_lo_u32_b32 v1, s4, 0
	v_mbcnt_hi_u32_b32 v1, s5, v1
	v_cmp_eq_u32_e32 vcc, 0, v1
	s_and_b64 s[6:7], exec, vcc
	s_mov_b64 exec, s[6:7]
	s_cbranch_execz .LBB0_11
	s_lshl_b32 s1, s67, 8
	s_bcnt1_i32_b64 s4, s[4:5]
	v_mov_b32_e32 v1, s1
	v_mov_b32_e32 v2, s4
	global_atomic_add v1, v2, s[78:79] offset:1024
